# b6 + P12 HID stores without the nt hint (P13 re-reads HID from the same XCD L2)
# speedup vs baseline: 1.0043x; 1.0005x over previous
.LBB0_1237:
	v_lshl_add_u32 v148, s38, 8, v150
	v_ashrrev_i32_e32 v149, 31, v148
	v_lshlrev_b64 v[144:145], 6, v[148:149]
	v_lshl_add_u64 v[144:145], s[14:15], 0, v[144:145]
	global_load_dwordx4 v[158:161], v[144:145], off
	global_load_dwordx4 v[162:165], v[144:145], off offset:16
	global_load_dwordx4 v[166:169], v[144:145], off offset:32
	global_load_dwordx4 v[170:173], v[144:145], off offset:48
	v_lshl_or_b32 v146, s8, 7, v152
	v_mov_b64_e32 v[144:145], s[12:13]
	v_ashrrev_i32_e32 v147, 31, v146
	v_mad_i64_i32 v[174:175], s[8:9], v148, s61, v[144:145]
	v_or_b32_e32 v176, 16, v148
	v_lshlrev_b64 v[146:147], 1, v[146:147]
	v_ashrrev_i32_e32 v177, 31, v176
	s_waitcnt vmcnt(0)
	v_pk_add_f32 v[160:161], v[160:161], v[164:165]
	v_pk_add_f32 v[158:159], v[158:159], v[162:163]
	v_pk_add_f32 v[162:163], v[168:169], v[172:173]
	v_pk_add_f32 v[164:165], v[166:167], v[170:171]
	v_pk_add_f32 v[160:161], v[160:161], v[162:163]
	v_pk_add_f32 v[158:159], v[158:159], v[164:165]
	s_nop 0
	v_pk_mov_b32 v[162:163], v[158:159], v[160:161] op_sel:[1,0]
	v_mov_b32_e32 v159, v161
	v_pk_add_f32 v[158:159], v[162:163], v[158:159]
	v_lshlrev_b64 v[160:161], 6, v[176:177]
	v_add_f32_e32 v149, v158, v159
	v_fmamk_f32 v149, v149, 0x3a800000, v156
	v_mul_f32_e32 v157, 0x4b800000, v149
	v_cmp_gt_f32_e32 vcc, s60, v149
	v_lshl_add_u64 v[158:159], v[174:175], 0, v[146:147]
	v_lshl_add_u64 v[160:161], s[14:15], 0, v[160:161]
	v_cndmask_b32_e32 v149, v149, v157, vcc
	v_rsq_f32_e32 v149, v149
	s_nop 0
	v_mul_f32_e32 v157, 0x45800000, v149
	v_cndmask_b32_e32 v162, v149, v157, vcc
	v_pk_mul_f32 v[124:125], v[124:125], v[162:163] op_sel_hi:[1,0]
	v_pk_mul_f32 v[126:127], v[126:127], v[162:163] op_sel_hi:[1,0]
	v_pk_mul_f32 v[120:121], v[120:121], v[162:163] op_sel_hi:[1,0]
	v_pk_mul_f32 v[122:123], v[122:123], v[162:163] op_sel_hi:[1,0]
	v_pk_mul_f32 v[116:117], v[116:117], v[162:163] op_sel_hi:[1,0]
	v_pk_mul_f32 v[118:119], v[118:119], v[162:163] op_sel_hi:[1,0]
	v_pk_mul_f32 v[112:113], v[112:113], v[162:163] op_sel_hi:[1,0]
	v_pk_mul_f32 v[114:115], v[114:115], v[162:163] op_sel_hi:[1,0]
	v_mul_f32_e32 v149, 0xbfb8aa3b, v124
	v_mul_f32_e32 v157, 0xbfb8aa3b, v125
	v_mul_f32_e32 v162, 0xbfb8aa3b, v126
	v_mul_f32_e32 v163, 0xbfb8aa3b, v127
	v_mul_f32_e32 v164, 0xbfb8aa3b, v120
	v_mul_f32_e32 v165, 0xbfb8aa3b, v121
	v_mul_f32_e32 v166, 0xbfb8aa3b, v122
	v_mul_f32_e32 v167, 0xbfb8aa3b, v123
	v_exp_f32_e32 v149, v149
	v_exp_f32_e32 v157, v157
	v_exp_f32_e32 v162, v162
	v_exp_f32_e32 v163, v163
	v_exp_f32_e32 v164, v164
	v_exp_f32_e32 v165, v165
	v_exp_f32_e32 v166, v166
	v_exp_f32_e32 v167, v167
	v_add_f32_e32 v149, 1.0, v149
	v_add_f32_e32 v157, 1.0, v157
	v_add_f32_e32 v168, 1.0, v162
	v_add_f32_e32 v169, 1.0, v163
	v_add_f32_e32 v170, 1.0, v164
	v_add_f32_e32 v171, 1.0, v165
	v_add_f32_e32 v172, 1.0, v166
	v_add_f32_e32 v173, 1.0, v167
	v_rcp_f32_e32 v162, v149
	v_rcp_f32_e32 v163, v157
	v_rcp_f32_e32 v164, v168
	v_rcp_f32_e32 v165, v169
	v_rcp_f32_e32 v166, v170
	v_rcp_f32_e32 v167, v171
	v_rcp_f32_e32 v168, v172
	v_rcp_f32_e32 v169, v173
	v_pk_mul_f32 v[124:125], v[124:125], v[162:163]
	v_pk_mul_f32 v[126:127], v[126:127], v[164:165]
	v_pk_mul_f32 v[120:121], v[120:121], v[166:167]
	v_pk_mul_f32 v[122:123], v[122:123], v[168:169]
	v_pk_mul_f32 v[116:117], v[116:117], v[124:125]
	v_pk_mul_f32 v[118:119], v[118:119], v[126:127]
	v_pk_mul_f32 v[120:121], v[112:113], v[120:121]
	v_pk_mul_f32 v[122:123], v[114:115], v[122:123]
	v_cvt_pk_bf16_f32 v112, v116, v117
	v_cvt_pk_bf16_f32 v113, v118, v119
	v_cvt_pk_bf16_f32 v114, v120, v121
	v_cvt_pk_bf16_f32 v115, v122, v123
	global_store_dwordx4 v[158:159], v[112:115], off
	global_load_dwordx4 v[112:115], v[160:161], off
	global_load_dwordx4 v[116:119], v[160:161], off offset:16
	global_load_dwordx4 v[120:123], v[160:161], off offset:32
	global_load_dwordx4 v[124:127], v[160:161], off offset:48
	v_or_b32_e32 v158, 32, v148
	v_mad_i64_i32 v[160:161], s[8:9], v176, s61, v[144:145]
	v_ashrrev_i32_e32 v159, 31, v158
	s_waitcnt vmcnt(2)
	v_pk_add_f32 v[114:115], v[114:115], v[118:119]
	v_pk_add_f32 v[112:113], v[112:113], v[116:117]
	s_waitcnt vmcnt(0)
	v_pk_add_f32 v[116:117], v[122:123], v[126:127]
	v_pk_add_f32 v[118:119], v[120:121], v[124:125]
	v_pk_add_f32 v[114:115], v[114:115], v[116:117]
	v_pk_add_f32 v[112:113], v[112:113], v[118:119]
	s_nop 0
	v_pk_mov_b32 v[116:117], v[112:113], v[114:115] op_sel:[1,0]
	v_mov_b32_e32 v113, v115
	v_pk_add_f32 v[112:113], v[116:117], v[112:113]
	v_lshlrev_b64 v[114:115], 6, v[158:159]
	v_add_f32_e32 v112, v112, v113
	v_fmamk_f32 v112, v112, 0x3a800000, v156
	v_mul_f32_e32 v113, 0x4b800000, v112
	v_cmp_gt_f32_e32 vcc, s60, v112
	v_lshl_add_u64 v[114:115], s[14:15], 0, v[114:115]
	s_nop 0
	v_cndmask_b32_e32 v112, v112, v113, vcc
	v_rsq_f32_e32 v116, v112
	v_lshl_add_u64 v[112:113], v[160:161], 0, v[146:147]
	v_mul_f32_e32 v117, 0x45800000, v116
	v_cndmask_b32_e32 v116, v116, v117, vcc
	v_pk_mul_f32 v[108:109], v[108:109], v[116:117] op_sel_hi:[1,0]
	v_pk_mul_f32 v[110:111], v[110:111], v[116:117] op_sel_hi:[1,0]
	v_pk_mul_f32 v[104:105], v[104:105], v[116:117] op_sel_hi:[1,0]
	v_pk_mul_f32 v[106:107], v[106:107], v[116:117] op_sel_hi:[1,0]
	v_pk_mul_f32 v[100:101], v[100:101], v[116:117] op_sel_hi:[1,0]
	v_pk_mul_f32 v[102:103], v[102:103], v[116:117] op_sel_hi:[1,0]
	v_pk_mul_f32 v[96:97], v[96:97], v[116:117] op_sel_hi:[1,0]
	v_pk_mul_f32 v[98:99], v[98:99], v[116:117] op_sel_hi:[1,0]
	v_mul_f32_e32 v116, 0xbfb8aa3b, v108
	v_mul_f32_e32 v117, 0xbfb8aa3b, v109
	v_mul_f32_e32 v118, 0xbfb8aa3b, v110
	v_mul_f32_e32 v119, 0xbfb8aa3b, v111
	v_mul_f32_e32 v120, 0xbfb8aa3b, v104
	v_mul_f32_e32 v121, 0xbfb8aa3b, v105
	v_mul_f32_e32 v122, 0xbfb8aa3b, v106
	v_mul_f32_e32 v123, 0xbfb8aa3b, v107
	v_exp_f32_e32 v116, v116
	v_exp_f32_e32 v117, v117
	v_exp_f32_e32 v118, v118
	v_exp_f32_e32 v119, v119
	v_exp_f32_e32 v120, v120
	v_exp_f32_e32 v121, v121
	v_exp_f32_e32 v122, v122
	v_exp_f32_e32 v123, v123
	v_add_f32_e32 v116, 1.0, v116
	v_add_f32_e32 v117, 1.0, v117
	v_add_f32_e32 v118, 1.0, v118
	v_add_f32_e32 v119, 1.0, v119
	v_add_f32_e32 v120, 1.0, v120
	v_add_f32_e32 v121, 1.0, v121
	v_add_f32_e32 v122, 1.0, v122
	v_add_f32_e32 v123, 1.0, v123
	v_rcp_f32_e32 v116, v116
	v_rcp_f32_e32 v117, v117
	v_rcp_f32_e32 v118, v118
	v_rcp_f32_e32 v119, v119
	v_rcp_f32_e32 v120, v120
	v_rcp_f32_e32 v121, v121
	v_rcp_f32_e32 v122, v122
	v_rcp_f32_e32 v123, v123
	v_pk_mul_f32 v[108:109], v[108:109], v[116:117]
	v_pk_mul_f32 v[110:111], v[110:111], v[118:119]
	v_pk_mul_f32 v[104:105], v[104:105], v[120:121]
	v_pk_mul_f32 v[106:107], v[106:107], v[122:123]
	v_pk_mul_f32 v[100:101], v[100:101], v[108:109]
	v_pk_mul_f32 v[102:103], v[102:103], v[110:111]
	v_pk_mul_f32 v[104:105], v[96:97], v[104:105]
	v_pk_mul_f32 v[106:107], v[98:99], v[106:107]
	v_cvt_pk_bf16_f32 v96, v100, v101
	v_cvt_pk_bf16_f32 v97, v102, v103
	v_cvt_pk_bf16_f32 v98, v104, v105
	v_cvt_pk_bf16_f32 v99, v106, v107
	global_store_dwordx4 v[112:113], v[96:99], off
	global_load_dwordx4 v[96:99], v[114:115], off
	global_load_dwordx4 v[100:103], v[114:115], off offset:16
	global_load_dwordx4 v[104:107], v[114:115], off offset:32
	global_load_dwordx4 v[108:111], v[114:115], off offset:48
	v_or_b32_e32 v112, 48, v148
	v_mad_i64_i32 v[114:115], s[8:9], v158, s61, v[144:145]
	v_ashrrev_i32_e32 v113, 31, v112
	s_waitcnt vmcnt(2)
	v_pk_add_f32 v[98:99], v[98:99], v[102:103]
	v_pk_add_f32 v[96:97], v[96:97], v[100:101]
	s_waitcnt vmcnt(0)
	v_pk_add_f32 v[100:101], v[106:107], v[110:111]
	v_pk_add_f32 v[102:103], v[104:105], v[108:109]
	v_pk_add_f32 v[98:99], v[98:99], v[100:101]
	v_pk_add_f32 v[96:97], v[96:97], v[102:103]
	s_nop 0
	v_pk_mov_b32 v[100:101], v[96:97], v[98:99] op_sel:[1,0]
	v_mov_b32_e32 v97, v99
	v_pk_add_f32 v[96:97], v[100:101], v[96:97]
	v_lshlrev_b64 v[98:99], 6, v[112:113]
	v_add_f32_e32 v96, v96, v97
	v_fmamk_f32 v96, v96, 0x3a800000, v156
	v_mul_f32_e32 v97, 0x4b800000, v96
	v_cmp_gt_f32_e32 vcc, s60, v96
	v_lshl_add_u64 v[98:99], s[14:15], 0, v[98:99]
	s_nop 0
	v_cndmask_b32_e32 v96, v96, v97, vcc
	v_rsq_f32_e32 v100, v96
	v_lshl_add_u64 v[96:97], v[114:115], 0, v[146:147]
	v_mul_f32_e32 v101, 0x45800000, v100
	v_cndmask_b32_e32 v100, v100, v101, vcc
	v_pk_mul_f32 v[92:93], v[92:93], v[100:101] op_sel_hi:[1,0]
	v_pk_mul_f32 v[94:95], v[94:95], v[100:101] op_sel_hi:[1,0]
	v_pk_mul_f32 v[88:89], v[88:89], v[100:101] op_sel_hi:[1,0]
	v_pk_mul_f32 v[90:91], v[90:91], v[100:101] op_sel_hi:[1,0]
	v_pk_mul_f32 v[84:85], v[84:85], v[100:101] op_sel_hi:[1,0]
	v_pk_mul_f32 v[86:87], v[86:87], v[100:101] op_sel_hi:[1,0]
	v_pk_mul_f32 v[80:81], v[80:81], v[100:101] op_sel_hi:[1,0]
	v_pk_mul_f32 v[82:83], v[82:83], v[100:101] op_sel_hi:[1,0]
	v_mul_f32_e32 v100, 0xbfb8aa3b, v92
	v_mul_f32_e32 v101, 0xbfb8aa3b, v93
	v_mul_f32_e32 v102, 0xbfb8aa3b, v94
	v_mul_f32_e32 v103, 0xbfb8aa3b, v95
	v_mul_f32_e32 v104, 0xbfb8aa3b, v88
	v_mul_f32_e32 v105, 0xbfb8aa3b, v89
	v_mul_f32_e32 v106, 0xbfb8aa3b, v90
	v_mul_f32_e32 v107, 0xbfb8aa3b, v91
	v_exp_f32_e32 v100, v100
	v_exp_f32_e32 v101, v101
	v_exp_f32_e32 v102, v102
	v_exp_f32_e32 v103, v103
	v_exp_f32_e32 v104, v104
	v_exp_f32_e32 v105, v105
	v_exp_f32_e32 v106, v106
	v_exp_f32_e32 v107, v107
	v_add_f32_e32 v100, 1.0, v100
	v_add_f32_e32 v101, 1.0, v101
	v_add_f32_e32 v102, 1.0, v102
	v_add_f32_e32 v103, 1.0, v103
	v_add_f32_e32 v104, 1.0, v104
	v_add_f32_e32 v105, 1.0, v105
	v_add_f32_e32 v106, 1.0, v106
	v_add_f32_e32 v107, 1.0, v107
	v_rcp_f32_e32 v100, v100
	v_rcp_f32_e32 v101, v101
	v_rcp_f32_e32 v102, v102
	v_rcp_f32_e32 v103, v103
	v_rcp_f32_e32 v104, v104
	v_rcp_f32_e32 v105, v105
	v_rcp_f32_e32 v106, v106
	v_rcp_f32_e32 v107, v107
	v_pk_mul_f32 v[92:93], v[92:93], v[100:101]
	v_pk_mul_f32 v[94:95], v[94:95], v[102:103]
	v_pk_mul_f32 v[88:89], v[88:89], v[104:105]
	v_pk_mul_f32 v[90:91], v[90:91], v[106:107]
	v_pk_mul_f32 v[84:85], v[84:85], v[92:93]
	v_pk_mul_f32 v[86:87], v[86:87], v[94:95]
	v_pk_mul_f32 v[88:89], v[80:81], v[88:89]
	v_pk_mul_f32 v[90:91], v[82:83], v[90:91]
	v_cvt_pk_bf16_f32 v80, v84, v85
	v_cvt_pk_bf16_f32 v81, v86, v87
	v_cvt_pk_bf16_f32 v82, v88, v89
	v_cvt_pk_bf16_f32 v83, v90, v91
	global_store_dwordx4 v[96:97], v[80:83], off
	global_load_dwordx4 v[80:83], v[98:99], off
	global_load_dwordx4 v[84:87], v[98:99], off offset:16
	global_load_dwordx4 v[88:91], v[98:99], off offset:32
	global_load_dwordx4 v[92:95], v[98:99], off offset:48
	v_add_u32_e32 v96, 0x80, v148
	v_mad_i64_i32 v[98:99], s[8:9], v112, s61, v[144:145]
	v_ashrrev_i32_e32 v97, 31, v96
	s_waitcnt vmcnt(2)
	v_pk_add_f32 v[82:83], v[82:83], v[86:87]
	v_pk_add_f32 v[80:81], v[80:81], v[84:85]
	s_waitcnt vmcnt(0)
	v_pk_add_f32 v[84:85], v[90:91], v[94:95]
	v_pk_add_f32 v[86:87], v[88:89], v[92:93]
	v_pk_add_f32 v[82:83], v[82:83], v[84:85]
	v_pk_add_f32 v[80:81], v[80:81], v[86:87]
	s_nop 0
	v_pk_mov_b32 v[84:85], v[80:81], v[82:83] op_sel:[1,0]
	v_mov_b32_e32 v81, v83
	v_pk_add_f32 v[80:81], v[84:85], v[80:81]
	v_lshlrev_b64 v[82:83], 6, v[96:97]
	v_add_f32_e32 v80, v80, v81
	v_fmamk_f32 v80, v80, 0x3a800000, v156
	v_mul_f32_e32 v81, 0x4b800000, v80
	v_cmp_gt_f32_e32 vcc, s60, v80
	v_lshl_add_u64 v[82:83], s[14:15], 0, v[82:83]
	s_nop 0
	v_cndmask_b32_e32 v80, v80, v81, vcc
	v_rsq_f32_e32 v84, v80
	v_lshl_add_u64 v[80:81], v[98:99], 0, v[146:147]
	v_mul_f32_e32 v85, 0x45800000, v84
	v_cndmask_b32_e32 v84, v84, v85, vcc
	v_pk_mul_f32 v[76:77], v[76:77], v[84:85] op_sel_hi:[1,0]
	v_pk_mul_f32 v[78:79], v[78:79], v[84:85] op_sel_hi:[1,0]
	v_pk_mul_f32 v[72:73], v[72:73], v[84:85] op_sel_hi:[1,0]
	v_pk_mul_f32 v[74:75], v[74:75], v[84:85] op_sel_hi:[1,0]
	v_pk_mul_f32 v[68:69], v[68:69], v[84:85] op_sel_hi:[1,0]
	v_pk_mul_f32 v[70:71], v[70:71], v[84:85] op_sel_hi:[1,0]
	v_pk_mul_f32 v[64:65], v[64:65], v[84:85] op_sel_hi:[1,0]
	v_pk_mul_f32 v[66:67], v[66:67], v[84:85] op_sel_hi:[1,0]
	v_mul_f32_e32 v84, 0xbfb8aa3b, v76
	v_mul_f32_e32 v85, 0xbfb8aa3b, v77
	v_mul_f32_e32 v86, 0xbfb8aa3b, v78
	v_mul_f32_e32 v87, 0xbfb8aa3b, v79
	v_mul_f32_e32 v88, 0xbfb8aa3b, v72
	v_mul_f32_e32 v89, 0xbfb8aa3b, v73
	v_mul_f32_e32 v90, 0xbfb8aa3b, v74
	v_mul_f32_e32 v91, 0xbfb8aa3b, v75
	v_exp_f32_e32 v84, v84
	v_exp_f32_e32 v85, v85
	v_exp_f32_e32 v86, v86
	v_exp_f32_e32 v87, v87
	v_exp_f32_e32 v88, v88
	v_exp_f32_e32 v89, v89
	v_exp_f32_e32 v90, v90
	v_exp_f32_e32 v91, v91
	v_add_f32_e32 v84, 1.0, v84
	v_add_f32_e32 v85, 1.0, v85
	v_add_f32_e32 v86, 1.0, v86
	v_add_f32_e32 v87, 1.0, v87
	v_add_f32_e32 v88, 1.0, v88
	v_add_f32_e32 v89, 1.0, v89
	v_add_f32_e32 v90, 1.0, v90
	v_add_f32_e32 v91, 1.0, v91
	v_rcp_f32_e32 v84, v84
	v_rcp_f32_e32 v85, v85
	v_rcp_f32_e32 v86, v86
	v_rcp_f32_e32 v87, v87
	v_rcp_f32_e32 v88, v88
	v_rcp_f32_e32 v89, v89
	v_rcp_f32_e32 v90, v90
	v_rcp_f32_e32 v91, v91
	v_pk_mul_f32 v[76:77], v[76:77], v[84:85]
	v_pk_mul_f32 v[78:79], v[78:79], v[86:87]
	v_pk_mul_f32 v[72:73], v[72:73], v[88:89]
	v_pk_mul_f32 v[74:75], v[74:75], v[90:91]
	v_pk_mul_f32 v[68:69], v[68:69], v[76:77]
	v_pk_mul_f32 v[70:71], v[70:71], v[78:79]
	v_pk_mul_f32 v[72:73], v[64:65], v[72:73]
	v_pk_mul_f32 v[74:75], v[66:67], v[74:75]
	v_cvt_pk_bf16_f32 v64, v68, v69
	v_cvt_pk_bf16_f32 v65, v70, v71
	v_cvt_pk_bf16_f32 v66, v72, v73
	v_cvt_pk_bf16_f32 v67, v74, v75
	global_store_dwordx4 v[80:81], v[64:67], off
	global_load_dwordx4 v[64:67], v[82:83], off
	global_load_dwordx4 v[68:71], v[82:83], off offset:16
	global_load_dwordx4 v[72:75], v[82:83], off offset:32
	global_load_dwordx4 v[76:79], v[82:83], off offset:48
	v_add_u32_e32 v80, 0x90, v148
	v_mad_i64_i32 v[82:83], s[8:9], v96, s61, v[144:145]
	v_ashrrev_i32_e32 v81, 31, v80
	s_waitcnt vmcnt(2)
	v_pk_add_f32 v[66:67], v[66:67], v[70:71]
	v_pk_add_f32 v[64:65], v[64:65], v[68:69]
	s_waitcnt vmcnt(0)
	v_pk_add_f32 v[68:69], v[74:75], v[78:79]
	v_pk_add_f32 v[70:71], v[72:73], v[76:77]
	v_pk_add_f32 v[66:67], v[66:67], v[68:69]
	v_pk_add_f32 v[64:65], v[64:65], v[70:71]
	s_nop 0
	v_pk_mov_b32 v[68:69], v[64:65], v[66:67] op_sel:[1,0]
	v_mov_b32_e32 v65, v67
	v_pk_add_f32 v[64:65], v[68:69], v[64:65]
	v_lshlrev_b64 v[66:67], 6, v[80:81]
	v_add_f32_e32 v64, v64, v65
	v_fmamk_f32 v64, v64, 0x3a800000, v156
	v_mul_f32_e32 v65, 0x4b800000, v64
	v_cmp_gt_f32_e32 vcc, s60, v64
	v_lshl_add_u64 v[66:67], s[14:15], 0, v[66:67]
	s_nop 0
	v_cndmask_b32_e32 v64, v64, v65, vcc
	v_rsq_f32_e32 v68, v64
	v_lshl_add_u64 v[64:65], v[82:83], 0, v[146:147]
	v_mul_f32_e32 v69, 0x45800000, v68
	v_cndmask_b32_e32 v68, v68, v69, vcc
	v_pk_mul_f32 v[60:61], v[60:61], v[68:69] op_sel_hi:[1,0]
	v_pk_mul_f32 v[62:63], v[62:63], v[68:69] op_sel_hi:[1,0]
	v_pk_mul_f32 v[56:57], v[56:57], v[68:69] op_sel_hi:[1,0]
	v_pk_mul_f32 v[58:59], v[58:59], v[68:69] op_sel_hi:[1,0]
	v_pk_mul_f32 v[52:53], v[52:53], v[68:69] op_sel_hi:[1,0]
	v_pk_mul_f32 v[54:55], v[54:55], v[68:69] op_sel_hi:[1,0]
	v_pk_mul_f32 v[48:49], v[48:49], v[68:69] op_sel_hi:[1,0]
	v_pk_mul_f32 v[50:51], v[50:51], v[68:69] op_sel_hi:[1,0]
	v_mul_f32_e32 v68, 0xbfb8aa3b, v60
	v_mul_f32_e32 v69, 0xbfb8aa3b, v61
	v_mul_f32_e32 v70, 0xbfb8aa3b, v62
	v_mul_f32_e32 v71, 0xbfb8aa3b, v63
	v_mul_f32_e32 v72, 0xbfb8aa3b, v56
	v_mul_f32_e32 v73, 0xbfb8aa3b, v57
	v_mul_f32_e32 v74, 0xbfb8aa3b, v58
	v_mul_f32_e32 v75, 0xbfb8aa3b, v59
	v_exp_f32_e32 v68, v68
	v_exp_f32_e32 v69, v69
	v_exp_f32_e32 v70, v70
	v_exp_f32_e32 v71, v71
	v_exp_f32_e32 v72, v72
	v_exp_f32_e32 v73, v73
	v_exp_f32_e32 v74, v74
	v_exp_f32_e32 v75, v75
	v_add_f32_e32 v68, 1.0, v68
	v_add_f32_e32 v69, 1.0, v69
	v_add_f32_e32 v70, 1.0, v70
	v_add_f32_e32 v71, 1.0, v71
	v_add_f32_e32 v72, 1.0, v72
	v_add_f32_e32 v73, 1.0, v73
	v_add_f32_e32 v74, 1.0, v74
	v_add_f32_e32 v75, 1.0, v75
	v_rcp_f32_e32 v68, v68
	v_rcp_f32_e32 v69, v69
	v_rcp_f32_e32 v70, v70
	v_rcp_f32_e32 v71, v71
	v_rcp_f32_e32 v72, v72
	v_rcp_f32_e32 v73, v73
	v_rcp_f32_e32 v74, v74
	v_rcp_f32_e32 v75, v75
	v_pk_mul_f32 v[60:61], v[60:61], v[68:69]
	v_pk_mul_f32 v[62:63], v[62:63], v[70:71]
	v_pk_mul_f32 v[56:57], v[56:57], v[72:73]
	v_pk_mul_f32 v[58:59], v[58:59], v[74:75]
	v_pk_mul_f32 v[52:53], v[52:53], v[60:61]
	v_pk_mul_f32 v[54:55], v[54:55], v[62:63]
	v_pk_mul_f32 v[56:57], v[48:49], v[56:57]
	v_pk_mul_f32 v[58:59], v[50:51], v[58:59]
	v_cvt_pk_bf16_f32 v48, v52, v53
	v_cvt_pk_bf16_f32 v49, v54, v55
	v_cvt_pk_bf16_f32 v50, v56, v57
	v_cvt_pk_bf16_f32 v51, v58, v59
	global_store_dwordx4 v[64:65], v[48:51], off
	global_load_dwordx4 v[48:51], v[66:67], off
	global_load_dwordx4 v[52:55], v[66:67], off offset:16
	global_load_dwordx4 v[56:59], v[66:67], off offset:32
	global_load_dwordx4 v[60:63], v[66:67], off offset:48
	v_add_u32_e32 v64, 0xa0, v148
	v_mad_i64_i32 v[66:67], s[8:9], v80, s61, v[144:145]
	v_ashrrev_i32_e32 v65, 31, v64
	s_waitcnt vmcnt(2)
	v_pk_add_f32 v[50:51], v[50:51], v[54:55]
	v_pk_add_f32 v[48:49], v[48:49], v[52:53]
	s_waitcnt vmcnt(0)
	v_pk_add_f32 v[52:53], v[58:59], v[62:63]
	v_pk_add_f32 v[54:55], v[56:57], v[60:61]
	v_pk_add_f32 v[50:51], v[50:51], v[52:53]
	v_pk_add_f32 v[48:49], v[48:49], v[54:55]
	s_nop 0
	v_pk_mov_b32 v[52:53], v[48:49], v[50:51] op_sel:[1,0]
	v_mov_b32_e32 v49, v51
	v_pk_add_f32 v[48:49], v[52:53], v[48:49]
	v_lshlrev_b64 v[50:51], 6, v[64:65]
	v_add_f32_e32 v48, v48, v49
	v_fmamk_f32 v48, v48, 0x3a800000, v156
	v_mul_f32_e32 v49, 0x4b800000, v48
	v_cmp_gt_f32_e32 vcc, s60, v48
	v_lshl_add_u64 v[50:51], s[14:15], 0, v[50:51]
	s_nop 0
	v_cndmask_b32_e32 v48, v48, v49, vcc
	v_rsq_f32_e32 v52, v48
	v_lshl_add_u64 v[48:49], v[66:67], 0, v[146:147]
	v_mul_f32_e32 v53, 0x45800000, v52
	v_cndmask_b32_e32 v52, v52, v53, vcc
	v_pk_mul_f32 v[44:45], v[44:45], v[52:53] op_sel_hi:[1,0]
	v_pk_mul_f32 v[46:47], v[46:47], v[52:53] op_sel_hi:[1,0]
	v_pk_mul_f32 v[40:41], v[40:41], v[52:53] op_sel_hi:[1,0]
	v_pk_mul_f32 v[42:43], v[42:43], v[52:53] op_sel_hi:[1,0]
	v_pk_mul_f32 v[36:37], v[36:37], v[52:53] op_sel_hi:[1,0]
	v_pk_mul_f32 v[38:39], v[38:39], v[52:53] op_sel_hi:[1,0]
	v_pk_mul_f32 v[32:33], v[32:33], v[52:53] op_sel_hi:[1,0]
	v_pk_mul_f32 v[34:35], v[34:35], v[52:53] op_sel_hi:[1,0]
	v_mul_f32_e32 v52, 0xbfb8aa3b, v44
	v_mul_f32_e32 v53, 0xbfb8aa3b, v45
	v_mul_f32_e32 v54, 0xbfb8aa3b, v46
	v_mul_f32_e32 v55, 0xbfb8aa3b, v47
	v_mul_f32_e32 v56, 0xbfb8aa3b, v40
	v_mul_f32_e32 v57, 0xbfb8aa3b, v41
	v_mul_f32_e32 v58, 0xbfb8aa3b, v42
	v_mul_f32_e32 v59, 0xbfb8aa3b, v43
	v_exp_f32_e32 v52, v52
	v_exp_f32_e32 v53, v53
	v_exp_f32_e32 v54, v54
	v_exp_f32_e32 v55, v55
	v_exp_f32_e32 v56, v56
	v_exp_f32_e32 v57, v57
	v_exp_f32_e32 v58, v58
	v_exp_f32_e32 v59, v59
	v_add_f32_e32 v52, 1.0, v52
	v_add_f32_e32 v53, 1.0, v53
	v_add_f32_e32 v54, 1.0, v54
	v_add_f32_e32 v55, 1.0, v55
	v_add_f32_e32 v56, 1.0, v56
	v_add_f32_e32 v57, 1.0, v57
	v_add_f32_e32 v58, 1.0, v58
	v_add_f32_e32 v59, 1.0, v59
	v_rcp_f32_e32 v52, v52
	v_rcp_f32_e32 v53, v53
	v_rcp_f32_e32 v54, v54
	v_rcp_f32_e32 v55, v55
	v_rcp_f32_e32 v56, v56
	v_rcp_f32_e32 v57, v57
	v_rcp_f32_e32 v58, v58
	v_rcp_f32_e32 v59, v59
	v_pk_mul_f32 v[44:45], v[44:45], v[52:53]
	v_pk_mul_f32 v[46:47], v[46:47], v[54:55]
	v_pk_mul_f32 v[40:41], v[40:41], v[56:57]
	v_pk_mul_f32 v[42:43], v[42:43], v[58:59]
	v_pk_mul_f32 v[36:37], v[36:37], v[44:45]
	v_pk_mul_f32 v[38:39], v[38:39], v[46:47]
	v_pk_mul_f32 v[40:41], v[32:33], v[40:41]
	v_pk_mul_f32 v[42:43], v[34:35], v[42:43]
	v_cvt_pk_bf16_f32 v32, v36, v37
	v_cvt_pk_bf16_f32 v33, v38, v39
	v_cvt_pk_bf16_f32 v34, v40, v41
	v_cvt_pk_bf16_f32 v35, v42, v43
	global_store_dwordx4 v[48:49], v[32:35], off
	global_load_dwordx4 v[32:35], v[50:51], off
	global_load_dwordx4 v[36:39], v[50:51], off offset:16
	global_load_dwordx4 v[40:43], v[50:51], off offset:32
	global_load_dwordx4 v[44:47], v[50:51], off offset:48
	v_add_u32_e32 v48, 0xb0, v148
	v_mad_i64_i32 v[50:51], s[8:9], v64, s61, v[144:145]
	v_ashrrev_i32_e32 v49, 31, v48
	s_waitcnt vmcnt(2)
	v_pk_add_f32 v[34:35], v[34:35], v[38:39]
	v_pk_add_f32 v[32:33], v[32:33], v[36:37]
	s_waitcnt vmcnt(0)
	v_pk_add_f32 v[36:37], v[42:43], v[46:47]
	v_pk_add_f32 v[38:39], v[40:41], v[44:45]
	v_pk_add_f32 v[34:35], v[34:35], v[36:37]
	v_pk_add_f32 v[32:33], v[32:33], v[38:39]
	s_nop 0
	v_pk_mov_b32 v[36:37], v[32:33], v[34:35] op_sel:[1,0]
	v_mov_b32_e32 v33, v35
	v_pk_add_f32 v[32:33], v[36:37], v[32:33]
	v_lshlrev_b64 v[34:35], 6, v[48:49]
	v_add_f32_e32 v32, v32, v33
	v_fmamk_f32 v32, v32, 0x3a800000, v156
	v_mul_f32_e32 v33, 0x4b800000, v32
	v_cmp_gt_f32_e32 vcc, s60, v32
	v_lshl_add_u64 v[34:35], s[14:15], 0, v[34:35]
	s_nop 0
	v_cndmask_b32_e32 v32, v32, v33, vcc
	v_rsq_f32_e32 v36, v32
	v_lshl_add_u64 v[32:33], v[50:51], 0, v[146:147]
	v_mul_f32_e32 v37, 0x45800000, v36
	v_cndmask_b32_e32 v36, v36, v37, vcc
	v_pk_mul_f32 v[28:29], v[28:29], v[36:37] op_sel_hi:[1,0]
	v_pk_mul_f32 v[30:31], v[30:31], v[36:37] op_sel_hi:[1,0]
	v_pk_mul_f32 v[24:25], v[24:25], v[36:37] op_sel_hi:[1,0]
	v_pk_mul_f32 v[26:27], v[26:27], v[36:37] op_sel_hi:[1,0]
	v_pk_mul_f32 v[20:21], v[20:21], v[36:37] op_sel_hi:[1,0]
	v_pk_mul_f32 v[22:23], v[22:23], v[36:37] op_sel_hi:[1,0]
	v_pk_mul_f32 v[16:17], v[16:17], v[36:37] op_sel_hi:[1,0]
	v_pk_mul_f32 v[18:19], v[18:19], v[36:37] op_sel_hi:[1,0]
	v_mul_f32_e32 v36, 0xbfb8aa3b, v28
	v_mul_f32_e32 v37, 0xbfb8aa3b, v29
	v_mul_f32_e32 v38, 0xbfb8aa3b, v30
	v_mul_f32_e32 v39, 0xbfb8aa3b, v31
	v_mul_f32_e32 v40, 0xbfb8aa3b, v24
	v_mul_f32_e32 v41, 0xbfb8aa3b, v25
	v_mul_f32_e32 v42, 0xbfb8aa3b, v26
	v_mul_f32_e32 v43, 0xbfb8aa3b, v27
	v_exp_f32_e32 v36, v36
	v_exp_f32_e32 v37, v37
	v_exp_f32_e32 v38, v38
	v_exp_f32_e32 v39, v39
	v_exp_f32_e32 v40, v40
	v_exp_f32_e32 v41, v41
	v_exp_f32_e32 v42, v42
	v_exp_f32_e32 v43, v43
	v_add_f32_e32 v36, 1.0, v36
	v_add_f32_e32 v37, 1.0, v37
	v_add_f32_e32 v38, 1.0, v38
	v_add_f32_e32 v39, 1.0, v39
	v_add_f32_e32 v40, 1.0, v40
	v_add_f32_e32 v41, 1.0, v41
	v_add_f32_e32 v42, 1.0, v42
	v_add_f32_e32 v43, 1.0, v43
	v_rcp_f32_e32 v36, v36
	v_rcp_f32_e32 v37, v37
	v_rcp_f32_e32 v38, v38
	v_rcp_f32_e32 v39, v39
	v_rcp_f32_e32 v40, v40
	v_rcp_f32_e32 v41, v41
	v_rcp_f32_e32 v42, v42
	v_rcp_f32_e32 v43, v43
	v_pk_mul_f32 v[28:29], v[28:29], v[36:37]
	v_pk_mul_f32 v[30:31], v[30:31], v[38:39]
	v_pk_mul_f32 v[24:25], v[24:25], v[40:41]
	v_pk_mul_f32 v[26:27], v[26:27], v[42:43]
	v_pk_mul_f32 v[20:21], v[20:21], v[28:29]
	v_pk_mul_f32 v[22:23], v[22:23], v[30:31]
	v_pk_mul_f32 v[24:25], v[16:17], v[24:25]
	v_pk_mul_f32 v[26:27], v[18:19], v[26:27]
	v_cvt_pk_bf16_f32 v16, v20, v21
	v_cvt_pk_bf16_f32 v17, v22, v23
	v_cvt_pk_bf16_f32 v18, v24, v25
	v_cvt_pk_bf16_f32 v19, v26, v27
	global_store_dwordx4 v[32:33], v[16:19], off
	global_load_dwordx4 v[16:19], v[34:35], off
	global_load_dwordx4 v[20:23], v[34:35], off offset:16
	global_load_dwordx4 v[24:27], v[34:35], off offset:32
	global_load_dwordx4 v[28:31], v[34:35], off offset:48
	s_waitcnt vmcnt(2)
	v_pk_add_f32 v[18:19], v[18:19], v[22:23]
	v_pk_add_f32 v[16:17], v[16:17], v[20:21]
	s_waitcnt vmcnt(0)
	v_pk_add_f32 v[20:21], v[26:27], v[30:31]
	v_pk_add_f32 v[22:23], v[24:25], v[28:29]
	v_pk_add_f32 v[18:19], v[18:19], v[20:21]
	v_pk_add_f32 v[16:17], v[16:17], v[22:23]
	s_nop 0
	v_pk_mov_b32 v[20:21], v[16:17], v[18:19] op_sel:[1,0]
	v_mov_b32_e32 v17, v19
	v_pk_add_f32 v[16:17], v[20:21], v[16:17]
	s_nop 0
	v_add_f32_e32 v16, v16, v17
	v_fmamk_f32 v16, v16, 0x3a800000, v156
	v_mul_f32_e32 v17, 0x4b800000, v16
	v_cmp_gt_f32_e32 vcc, s60, v16
	s_nop 1
	v_cndmask_b32_e32 v16, v16, v17, vcc
	v_rsq_f32_e32 v18, v16
	v_mad_i64_i32 v[16:17], s[8:9], v48, s61, v[144:145]
	v_lshl_add_u64 v[16:17], v[16:17], 0, v[146:147]
	v_mul_f32_e32 v19, 0x45800000, v18
	v_cndmask_b32_e32 v18, v18, v19, vcc
	v_pk_mul_f32 v[12:13], v[12:13], v[18:19] op_sel_hi:[1,0]
	v_pk_mul_f32 v[14:15], v[14:15], v[18:19] op_sel_hi:[1,0]
	v_pk_mul_f32 v[8:9], v[8:9], v[18:19] op_sel_hi:[1,0]
	v_pk_mul_f32 v[10:11], v[10:11], v[18:19] op_sel_hi:[1,0]
	v_pk_mul_f32 v[4:5], v[4:5], v[18:19] op_sel_hi:[1,0]
	v_pk_mul_f32 v[6:7], v[6:7], v[18:19] op_sel_hi:[1,0]
	v_pk_mul_f32 v[0:1], v[0:1], v[18:19] op_sel_hi:[1,0]
	v_pk_mul_f32 v[2:3], v[2:3], v[18:19] op_sel_hi:[1,0]
	v_mul_f32_e32 v18, 0xbfb8aa3b, v12
	v_mul_f32_e32 v19, 0xbfb8aa3b, v13
	v_mul_f32_e32 v20, 0xbfb8aa3b, v14
	v_mul_f32_e32 v21, 0xbfb8aa3b, v15
	v_mul_f32_e32 v22, 0xbfb8aa3b, v8
	v_mul_f32_e32 v23, 0xbfb8aa3b, v9
	v_mul_f32_e32 v24, 0xbfb8aa3b, v10
	v_mul_f32_e32 v25, 0xbfb8aa3b, v11
	v_exp_f32_e32 v18, v18
	v_exp_f32_e32 v19, v19
	v_exp_f32_e32 v20, v20
	v_exp_f32_e32 v21, v21
	v_exp_f32_e32 v22, v22
	v_exp_f32_e32 v23, v23
	v_exp_f32_e32 v24, v24
	v_exp_f32_e32 v25, v25
	v_add_f32_e32 v18, 1.0, v18
	v_add_f32_e32 v19, 1.0, v19
	v_add_f32_e32 v20, 1.0, v20
	v_add_f32_e32 v21, 1.0, v21
	v_add_f32_e32 v22, 1.0, v22
	v_add_f32_e32 v23, 1.0, v23
	v_add_f32_e32 v24, 1.0, v24
	v_add_f32_e32 v25, 1.0, v25
	v_rcp_f32_e32 v18, v18
	v_rcp_f32_e32 v19, v19
	v_rcp_f32_e32 v20, v20
	v_rcp_f32_e32 v21, v21
	v_rcp_f32_e32 v22, v22
	v_rcp_f32_e32 v23, v23
	v_rcp_f32_e32 v24, v24
	v_rcp_f32_e32 v25, v25
	v_pk_mul_f32 v[12:13], v[12:13], v[18:19]
	v_pk_mul_f32 v[14:15], v[14:15], v[20:21]
	v_pk_mul_f32 v[8:9], v[8:9], v[22:23]
	v_pk_mul_f32 v[10:11], v[10:11], v[24:25]
	v_pk_mul_f32 v[4:5], v[4:5], v[12:13]
	v_pk_mul_f32 v[6:7], v[6:7], v[14:15]
	v_pk_mul_f32 v[8:9], v[0:1], v[8:9]
	v_pk_mul_f32 v[10:11], v[2:3], v[10:11]
	v_cvt_pk_bf16_f32 v0, v4, v5
	v_cvt_pk_bf16_f32 v1, v6, v7
	v_cvt_pk_bf16_f32 v2, v8, v9
	v_cvt_pk_bf16_f32 v3, v10, v11
	global_store_dwordx4 v[16:17], v[0:3], off
	s_andn2_b64 vcc, exec, s[6:7]
	s_mov_b64 s[6:7], -1
	s_cbranch_vccnz .LBB0_1230
	s_andn2_b64 vcc, exec, s[0:1]
	s_cbranch_vccnz .LBB0_1229
	s_barrier
	s_branch .LBB0_1229
